# baseline (speedup 1.0000x reference)
; #define STAGE(Pp, BASE, br, kt) do { const u16* _g = (BASE) + ((long)(br) * K + (long)(kt) * BK); \
;     __builtin_amdgcn_global_load_lds((const unsigned*)(_g + voff0), (unsigned*)((char*)(Pp) + tb16), 16, 0, 0); \
;     __builtin_amdgcn_global_load_lds((const unsigned*)(_g + voff1), (unsigned*)((char*)(Pp) + tb16 + 8192), 16, 0, 0); } while (0)
; #define WAIT_V(n) asm volatile("s_waitcnt vmcnt(" #n ")" ::: "memory")
; #define BAR __builtin_amdgcn_s_barrier()
; template <int MODE> ...
;     ...
;   for (int wg0 = vb; wg0 < nwg; wg0 += nvb) {
;     int wgid = wg0;
;     { int q = nwg / NXCD, r = nwg % NXCD, xcd = wgid % NXCD, off = wgid / NXCD;
;       wgid = (xcd < r ? xcd * (q + 1) : r * (q + 1) + (xcd - r) * q) + off; }
;     int nig = WGM * nN, gid = wgid / nig, fm = gid * WGM, gsz = min(nM - fm, WGM);
;     int pm = fm + ((wgid % nig) % gsz), pn = (wgid % nig) / gsz, brow = pm * BM, bcol = pn * BM;
;     f32x4 acc[2][2][4][2] = {};
;     bf16x8 At[4][2], B0[2][2], B1[2][2];
;     ...
;     STAGE(SB(0, 0), Bt, bcol, 0); STAGE(SA(0, 0), A, brow, 0); STAGE(SB(0, 1), Bt, bcol + HALF, 0); STAGE(SA(0, 1), A, brow + HALF, 0);
;     STAGE(SB(1, 0), Bt, bcol, 1); STAGE(SA(1, 0), A, brow, 1); STAGE(SB(1, 1), Bt, bcol + HALF, 1);
;     WAIT_V(6);
;     if (wr == 1) BAR;
;     BAR;
.LBB0_151:
	s_ashr_i32 s66, s82, 31
	s_lshr_b32 s66, s66, 29
	s_add_i32 s66, s82, s66
	s_ashr_i32 s67, s66, 3
	s_and_b32 s66, s66, -8
	s_sub_i32 s66, s82, s66
	s_cmp_lt_i32 s66, 0
	s_cselect_b32 s68, s35, 0xd0
	s_mul_i32 s66, s68, s66
	s_add_i32 s66, s66, s67
	s_mul_hi_i32 s67, s66, 0x4ec4ec4f
	s_lshr_b32 s68, s67, 31
	s_ashr_i32 s67, s67, 7
	s_add_i32 s67, s67, s68
	s_mul_i32 s68, s67, 0x1a0
	s_sub_i32 s83, s66, s68
	s_sext_i32_i16 s66, s83
	s_bfe_u32 s66, s66, 0x3001c
	s_add_i32 s66, s83, s66
	s_sext_i32_i16 s69, s66
	s_and_b32 s66, s66, 0xfff8
	s_sub_i32 s66, s83, s66
	s_sext_i32_i16 s66, s66
	s_lshl_b32 s67, s67, 11
	s_lshl_b32 s66, s66, 8
	s_add_i32 s68, s66, s67
	s_lshl_b32 s66, s69, 5
	s_and_b32 s66, s66, 0xffffff00
	s_ashr_i32 s67, s66, 31
	s_lshl_b64 s[74:75], s[66:67], 13
	s_add_u32 s70, s3, s74
	v_readfirstlane_b32 s69, v153
	s_addc_u32 s71, s15, s75
	s_mov_b32 m0, s69
	v_readfirstlane_b32 s69, v154
	global_load_lds_dwordx4 v134, s[70:71]
	s_mov_b32 m0, s69
	s_ashr_i32 s69, s68, 31
	s_lshl_b64 s[76:77], s[68:69], 13
	v_lshl_add_u64 v[0:1], s[70:71], 0, v[134:135]
	v_lshl_add_u64 v[2:3], s[70:71], 0, v[136:137]
	global_load_lds_dwordx4 v136, s[70:71]
	s_add_u32 s70, s56, s76
	v_readfirstlane_b32 s69, v152
	s_addc_u32 s71, s57, s77
	s_mov_b32 m0, s69
	v_readfirstlane_b32 s69, v155
	global_load_lds_dwordx4 v134, s[70:71]
	s_mov_b32 m0, s69
	v_lshl_add_u64 v[4:5], s[70:71], 0, v[134:135]
	v_lshl_add_u64 v[6:7], s[70:71], 0, v[136:137]
	global_load_lds_dwordx4 v136, s[70:71]
	s_or_b32 s70, s66, 0x80
	s_ashr_i32 s71, s70, 31
	s_lshl_b64 s[70:71], s[70:71], 13
	s_add_u32 s70, s3, s70
	v_readfirstlane_b32 s69, v156
	s_addc_u32 s71, s15, s71
	s_mov_b32 m0, s69
	v_readfirstlane_b32 s69, v157
	global_load_lds_dwordx4 v134, s[70:71]
	s_mov_b32 m0, s69
	v_lshl_add_u64 v[8:9], s[70:71], 0, v[134:135]
	v_lshl_add_u64 v[10:11], s[70:71], 0, v[136:137]
	global_load_lds_dwordx4 v136, s[70:71]
	s_or_b32 s70, s68, 0x80
	s_ashr_i32 s71, s70, 31
	s_lshl_b64 s[72:73], s[70:71], 13
	s_add_u32 s72, s56, s72
	v_readfirstlane_b32 s69, v158
	s_addc_u32 s73, s57, s73
	s_mov_b32 m0, s69
	v_readfirstlane_b32 s69, v159
	global_load_lds_dwordx4 v134, s[72:73]
	s_mov_b32 m0, s69
	v_readfirstlane_b32 s69, v160
	global_load_lds_dwordx4 v136, s[72:73]
	v_lshl_add_u64 v[0:1], v[0:1], 0, s[38:39]
	s_mov_b32 m0, s69
	v_readfirstlane_b32 s69, v161
	global_load_lds_dwordx4 v[0:1], off
	v_lshl_add_u64 v[0:1], v[2:3], 0, s[38:39]
	s_mov_b32 m0, s69
	v_readfirstlane_b32 s69, v162
	global_load_lds_dwordx4 v[0:1], off
	v_lshl_add_u64 v[0:1], v[4:5], 0, s[38:39]
	s_mov_b32 m0, s69
	v_readfirstlane_b32 s69, v163
	global_load_lds_dwordx4 v[0:1], off
	v_lshl_add_u64 v[0:1], v[6:7], 0, s[38:39]
	s_mov_b32 m0, s69
	v_readfirstlane_b32 s69, v165
	global_load_lds_dwordx4 v[0:1], off
	v_lshl_add_u64 v[0:1], v[8:9], 0, s[38:39]
	s_mov_b32 m0, s69
	v_readfirstlane_b32 s69, v166
	global_load_lds_dwordx4 v[0:1], off
	v_lshl_add_u64 v[0:1], v[10:11], 0, s[38:39]
	s_mov_b32 m0, s69
	s_nop 0
	global_load_lds_dwordx4 v[0:1], off
	v_mov_b32_e32 v0, 0
	v_mov_b32_e32 v1, v0
	v_mov_b32_e32 v2, v0
	v_mov_b32_e32 v3, v0
	v_mov_b32_e32 v4, v0
	v_mov_b32_e32 v5, v0
	v_mov_b32_e32 v6, v0
	v_mov_b32_e32 v7, v0
	v_mov_b32_e32 v8, v0
	v_mov_b32_e32 v9, v0
	v_mov_b32_e32 v10, v0
	v_mov_b32_e32 v11, v0
	v_mov_b32_e32 v12, v0
	v_mov_b32_e32 v13, v0
	v_mov_b32_e32 v14, v0
	v_mov_b32_e32 v15, v0
	v_mov_b32_e32 v16, v0
	v_mov_b32_e32 v17, v0
	v_mov_b32_e32 v18, v0
	v_mov_b32_e32 v19, v0
	v_mov_b32_e32 v20, v0
	v_mov_b32_e32 v21, v0
	v_mov_b32_e32 v22, v0
	v_mov_b32_e32 v23, v0
	v_mov_b32_e32 v24, v0
	v_mov_b32_e32 v25, v0
	v_mov_b32_e32 v26, v0
	v_mov_b32_e32 v27, v0
	v_mov_b32_e32 v28, v0
	v_mov_b32_e32 v29, v0
	v_mov_b32_e32 v30, v0
	v_mov_b32_e32 v31, v0
	v_mov_b32_e32 v32, v0
	v_mov_b32_e32 v33, v0
	v_mov_b32_e32 v34, v0
	v_mov_b32_e32 v35, v0
	v_mov_b32_e32 v36, v0
	v_mov_b32_e32 v37, v0
	v_mov_b32_e32 v38, v0
	v_mov_b32_e32 v39, v0
	v_mov_b32_e32 v40, v0
	v_mov_b32_e32 v41, v0
	v_mov_b32_e32 v42, v0
	v_mov_b32_e32 v43, v0
	v_mov_b32_e32 v44, v0
	v_mov_b32_e32 v45, v0
	v_mov_b32_e32 v46, v0
	v_mov_b32_e32 v47, v0
	v_mov_b32_e32 v48, v0
	v_mov_b32_e32 v49, v0
	v_mov_b32_e32 v50, v0
	v_mov_b32_e32 v51, v0
	v_mov_b32_e32 v52, v0
	v_mov_b32_e32 v53, v0
	v_mov_b32_e32 v54, v0
	v_mov_b32_e32 v55, v0
	v_mov_b32_e32 v56, v0
	v_mov_b32_e32 v57, v0
	v_mov_b32_e32 v58, v0
	v_mov_b32_e32 v59, v0
	v_mov_b32_e32 v60, v0
	v_mov_b32_e32 v61, v0
	v_mov_b32_e32 v62, v0
	v_mov_b32_e32 v63, v0
	v_mov_b32_e32 v64, v0
	v_mov_b32_e32 v65, v0
	v_mov_b32_e32 v66, v0
	v_mov_b32_e32 v67, v0
	v_mov_b32_e32 v68, v0
	v_mov_b32_e32 v69, v0
	v_mov_b32_e32 v70, v0
	v_mov_b32_e32 v71, v0
	v_mov_b32_e32 v72, v0
	v_mov_b32_e32 v73, v0
	v_mov_b32_e32 v74, v0
	v_mov_b32_e32 v75, v0
	v_mov_b32_e32 v76, v0
	v_mov_b32_e32 v77, v0
	v_mov_b32_e32 v78, v0
	v_mov_b32_e32 v79, v0
	v_mov_b32_e32 v80, v0
	v_mov_b32_e32 v81, v0
	v_mov_b32_e32 v82, v0
	v_mov_b32_e32 v83, v0
	v_mov_b32_e32 v84, v0
	v_mov_b32_e32 v85, v0
	v_mov_b32_e32 v86, v0
	v_mov_b32_e32 v87, v0
	v_mov_b32_e32 v88, v0
	v_mov_b32_e32 v89, v0
	v_mov_b32_e32 v90, v0
	v_mov_b32_e32 v91, v0
	v_mov_b32_e32 v92, v0
	v_mov_b32_e32 v93, v0
	v_mov_b32_e32 v94, v0
	v_mov_b32_e32 v95, v0
	v_mov_b32_e32 v96, v0
	v_mov_b32_e32 v97, v0
	v_mov_b32_e32 v98, v0
	v_mov_b32_e32 v99, v0
	v_mov_b32_e32 v100, v0
	v_mov_b32_e32 v101, v0
	v_mov_b32_e32 v102, v0
	v_mov_b32_e32 v103, v0
	v_mov_b32_e32 v104, v0
	v_mov_b32_e32 v105, v0
	v_mov_b32_e32 v106, v0
	v_mov_b32_e32 v107, v0
	v_mov_b32_e32 v108, v0
	v_mov_b32_e32 v109, v0
	v_mov_b32_e32 v110, v0
	v_mov_b32_e32 v111, v0
	v_mov_b32_e32 v112, v0
	v_mov_b32_e32 v113, v0
	v_mov_b32_e32 v114, v0
	v_mov_b32_e32 v115, v0
	v_mov_b32_e32 v116, v0
	v_mov_b32_e32 v117, v0
	v_mov_b32_e32 v118, v0
	v_mov_b32_e32 v119, v0
	v_mov_b32_e32 v120, v0
	v_mov_b32_e32 v121, v0
	v_mov_b32_e32 v122, v0
	v_mov_b32_e32 v123, v0
	v_mov_b32_e32 v124, v0
	v_mov_b32_e32 v125, v0
	v_mov_b32_e32 v126, v0
	v_mov_b32_e32 v127, v0
	s_waitcnt vmcnt(6)
	s_and_saveexec_b64 s[78:79], s[4:5]
	s_cbranch_execz .LBB0_153
	s_barrier
.LBB0_153:
	s_or_b64 exec, exec, s[78:79]
	v_lshl_add_u64 v[138:139], v[130:131], 0, s[74:75]
	v_lshl_add_u64 v[140:141], v[132:133], 0, s[74:75]
	v_lshl_add_u64 v[142:143], v[130:131], 0, s[76:77]
	v_lshl_add_u64 v[144:145], v[132:133], 0, s[76:77]
	s_mov_b32 s69, -2
	s_mov_b64 s[74:75], s[56:57]
	s_barrier

; #define STAGE(Pp, BASE, br, kt) do { const u16* _g = (BASE) + ((long)(br) * K + (long)(kt) * BK); \
;     __builtin_amdgcn_global_load_lds((const unsigned*)(_g + voff0), (unsigned*)((char*)(Pp) + tb16), 16, 0, 0); \
;     __builtin_amdgcn_global_load_lds((const unsigned*)(_g + voff1), (unsigned*)((char*)(Pp) + tb16 + 8192), 16, 0, 0); } while (0)
; #define WAIT_V(n) asm volatile("s_waitcnt vmcnt(" #n ")" ::: "memory")
; #define BAR __builtin_amdgcn_s_barrier()
; template <int MODE> ...
;     ...
;   for (int wg0 = vb; wg0 < nwg; wg0 += nvb) {
;     int wgid = wg0;
;     { int q = nwg / NXCD, r = nwg % NXCD, xcd = wgid % NXCD, off = wgid / NXCD;
;       wgid = (xcd < r ? xcd * (q + 1) : r * (q + 1) + (xcd - r) * q) + off; }
;     int nig = WGM * nN, gid = wgid / nig, fm = gid * WGM, gsz = min(nM - fm, WGM);
;     int pm = fm + ((wgid % nig) % gsz), pn = (wgid % nig) / gsz, brow = pm * BM, bcol = pn * BM;
;     f32x4 acc[2][2][4][2] = {};
;     bf16x8 At[4][2], B0[2][2], B1[2][2];
;     ...
;     STAGE(SB(0, 0), Bt, bcol, 0); STAGE(SA(0, 0), A, brow, 0); STAGE(SB(0, 1), Bt, bcol + HALF, 0); STAGE(SA(0, 1), A, brow + HALF, 0);
;     STAGE(SB(1, 0), Bt, bcol, 1); STAGE(SA(1, 0), A, brow, 1); STAGE(SB(1, 1), Bt, bcol + HALF, 1);
;     WAIT_V(6);
;     if (wr == 1) BAR;
;     BAR;
.LBB0_174:
	s_ashr_i32 s62, s64, 3
	s_add_i32 s62, s66, s62
	s_ashr_i32 s63, s62, 31
	s_lshr_b32 s63, s63, 26
	s_add_i32 s63, s62, s63
	s_ashr_i32 s75, s63, 6
	s_lshl_b32 s64, s75, 3
	s_sub_i32 s65, 2, s64
	s_andn2_b32 s63, s63, 63
	s_min_u32 s65, s65, 8
	s_sub_i32 s66, s62, s63
	s_sext_i32_i8 s62, s66
	v_cvt_f32_ubyte0_e32 v1, s65
	v_cvt_f32_i32_e32 v0, s62
	v_rcp_iflag_f32_e32 v2, v1
	s_ashr_i32 s62, s62, 30
	s_or_b32 s67, s62, 1
	v_readfirstlane_b32 s70, v151
	v_mul_f32_e32 v2, v0, v2
	v_trunc_f32_e32 v2, v2
	v_fma_f32 v0, -v2, v1, v0
	v_cvt_i32_f32_e32 v2, v2
	v_cmp_ge_f32_e64 s[62:63], |v0|, v1
	s_and_b64 s[62:63], s[62:63], exec
	s_cselect_b32 s62, s67, 0
	v_readfirstlane_b32 s63, v2
	s_add_i32 s62, s63, s62
	s_sext_i32_i8 s63, s62
	s_mul_i32 s62, s62, s65
	s_sub_i32 s62, s66, s62
	s_sext_i32_i8 s76, s62
	s_lshl_b32 s62, s63, 8
	s_add_i32 s64, s64, s76
	s_ashr_i32 s63, s62, 31
	s_lshl_b32 s64, s64, 8
	s_lshl_b64 s[68:69], s[62:63], 13
	s_add_u32 s66, s34, s68
	v_readfirstlane_b32 s65, v150
	s_addc_u32 s67, s35, s69
	s_mov_b32 m0, s65
	v_readfirstlane_b32 s65, v152
	global_load_lds_dwordx4 v134, s[66:67]
	s_mov_b32 m0, s65
	s_ashr_i32 s65, s64, 31
	v_lshl_add_u64 v[0:1], s[66:67], 0, v[134:135]
	v_lshl_add_u64 v[2:3], s[66:67], 0, v[136:137]
	global_load_lds_dwordx4 v136, s[66:67]
	s_lshl_b64 s[66:67], s[64:65], 13
	s_add_u32 s66, s15, s66
	s_addc_u32 s67, s33, s67
	s_mov_b32 m0, s70
	v_readfirstlane_b32 s70, v153
	global_load_lds_dwordx4 v134, s[66:67]
	s_mov_b32 m0, s70
	v_lshl_add_u64 v[4:5], s[66:67], 0, v[134:135]
	v_lshl_add_u64 v[6:7], s[66:67], 0, v[136:137]
	global_load_lds_dwordx4 v136, s[66:67]
	s_or_b32 s66, s62, 0x80
	s_ashr_i32 s67, s66, 31
	s_lshl_b64 s[66:67], s[66:67], 13
	s_add_u32 s66, s34, s66
	v_readfirstlane_b32 s70, v154
	s_addc_u32 s67, s35, s67
	s_mov_b32 m0, s70
	v_readfirstlane_b32 s70, v155
	global_load_lds_dwordx4 v134, s[66:67]
	s_mov_b32 m0, s70
	v_lshl_add_u64 v[8:9], s[66:67], 0, v[134:135]
	v_lshl_add_u64 v[10:11], s[66:67], 0, v[136:137]
	global_load_lds_dwordx4 v136, s[66:67]
	s_or_b32 s66, s64, 0x80
	s_ashr_i32 s67, s66, 31
	s_lshl_b64 s[66:67], s[66:67], 13
	s_add_u32 s66, s15, s66
	v_readfirstlane_b32 s70, v156
	s_addc_u32 s67, s33, s67
	s_mov_b32 m0, s70
	v_readfirstlane_b32 s70, v157
	global_load_lds_dwordx4 v134, s[66:67]
	s_mov_b32 m0, s70
	v_readfirstlane_b32 s70, v158
	global_load_lds_dwordx4 v136, s[66:67]
	v_lshl_add_u64 v[0:1], v[0:1], 0, s[10:11]
	s_mov_b32 m0, s70
	v_readfirstlane_b32 s70, v159
	global_load_lds_dwordx4 v[0:1], off
	v_lshl_add_u64 v[0:1], v[2:3], 0, s[10:11]
	s_mov_b32 m0, s70
	v_readfirstlane_b32 s70, v160
	global_load_lds_dwordx4 v[0:1], off
	v_lshl_add_u64 v[0:1], v[4:5], 0, s[10:11]
	s_mov_b32 m0, s70
	v_readfirstlane_b32 s70, v161
	global_load_lds_dwordx4 v[0:1], off
	v_lshl_add_u64 v[0:1], v[6:7], 0, s[10:11]
	s_mov_b32 m0, s70
	v_readfirstlane_b32 s70, v162
	global_load_lds_dwordx4 v[0:1], off
	v_lshl_add_u64 v[0:1], v[8:9], 0, s[10:11]
	s_mov_b32 m0, s70
	v_readfirstlane_b32 s70, v163
	global_load_lds_dwordx4 v[0:1], off
	v_lshl_add_u64 v[0:1], v[10:11], 0, s[10:11]
	s_mov_b32 m0, s70
	s_nop 0
	global_load_lds_dwordx4 v[0:1], off
	v_mov_b32_e32 v0, 0
	v_mov_b32_e32 v1, v0
	v_mov_b32_e32 v2, v0
	v_mov_b32_e32 v3, v0
	v_mov_b32_e32 v4, v0
	v_mov_b32_e32 v5, v0
	v_mov_b32_e32 v6, v0
	v_mov_b32_e32 v7, v0
	v_mov_b32_e32 v8, v0
	v_mov_b32_e32 v9, v0
	v_mov_b32_e32 v10, v0
	v_mov_b32_e32 v11, v0
	v_mov_b32_e32 v12, v0
	v_mov_b32_e32 v13, v0
	v_mov_b32_e32 v14, v0
	v_mov_b32_e32 v15, v0
	v_mov_b32_e32 v16, v0
	v_mov_b32_e32 v17, v0
	v_mov_b32_e32 v18, v0
	v_mov_b32_e32 v19, v0
	v_mov_b32_e32 v20, v0
	v_mov_b32_e32 v21, v0
	v_mov_b32_e32 v22, v0
	v_mov_b32_e32 v23, v0
	v_mov_b32_e32 v24, v0
	v_mov_b32_e32 v25, v0
	v_mov_b32_e32 v26, v0
	v_mov_b32_e32 v27, v0
	v_mov_b32_e32 v28, v0
	v_mov_b32_e32 v29, v0
	v_mov_b32_e32 v30, v0
	v_mov_b32_e32 v31, v0
	v_mov_b32_e32 v32, v0
	v_mov_b32_e32 v33, v0
	v_mov_b32_e32 v34, v0
	v_mov_b32_e32 v35, v0
	v_mov_b32_e32 v36, v0
	v_mov_b32_e32 v37, v0
	v_mov_b32_e32 v38, v0
	v_mov_b32_e32 v39, v0
	v_mov_b32_e32 v40, v0
	v_mov_b32_e32 v41, v0
	v_mov_b32_e32 v42, v0
	v_mov_b32_e32 v43, v0
	v_mov_b32_e32 v44, v0
	v_mov_b32_e32 v45, v0
	v_mov_b32_e32 v46, v0
	v_mov_b32_e32 v47, v0
	v_mov_b32_e32 v48, v0
	v_mov_b32_e32 v49, v0
	v_mov_b32_e32 v50, v0
	v_mov_b32_e32 v51, v0
	v_mov_b32_e32 v52, v0
	v_mov_b32_e32 v53, v0
	v_mov_b32_e32 v54, v0
	v_mov_b32_e32 v55, v0
	v_mov_b32_e32 v56, v0
	v_mov_b32_e32 v57, v0
	v_mov_b32_e32 v58, v0
	v_mov_b32_e32 v59, v0
	v_mov_b32_e32 v60, v0
	v_mov_b32_e32 v61, v0
	v_mov_b32_e32 v62, v0
	v_mov_b32_e32 v63, v0
	v_mov_b32_e32 v64, v0
	v_mov_b32_e32 v65, v0
	v_mov_b32_e32 v66, v0
	v_mov_b32_e32 v67, v0
	v_mov_b32_e32 v68, v0
	v_mov_b32_e32 v69, v0
	v_mov_b32_e32 v70, v0
	v_mov_b32_e32 v71, v0
	v_mov_b32_e32 v72, v0
	v_mov_b32_e32 v73, v0
	v_mov_b32_e32 v74, v0
	v_mov_b32_e32 v75, v0
	v_mov_b32_e32 v76, v0
	v_mov_b32_e32 v77, v0
	v_mov_b32_e32 v78, v0
	v_mov_b32_e32 v79, v0
	v_mov_b32_e32 v80, v0
	v_mov_b32_e32 v81, v0
	v_mov_b32_e32 v82, v0
	v_mov_b32_e32 v83, v0
	v_mov_b32_e32 v84, v0
	v_mov_b32_e32 v85, v0
	v_mov_b32_e32 v86, v0
	v_mov_b32_e32 v87, v0
	v_mov_b32_e32 v88, v0
	v_mov_b32_e32 v89, v0
	v_mov_b32_e32 v90, v0
	v_mov_b32_e32 v91, v0
	v_mov_b32_e32 v92, v0
	v_mov_b32_e32 v93, v0
	v_mov_b32_e32 v94, v0
	v_mov_b32_e32 v95, v0
	v_mov_b32_e32 v96, v0
	v_mov_b32_e32 v97, v0
	v_mov_b32_e32 v98, v0
	v_mov_b32_e32 v99, v0
	v_mov_b32_e32 v100, v0
	v_mov_b32_e32 v101, v0
	v_mov_b32_e32 v102, v0
	v_mov_b32_e32 v103, v0
	v_mov_b32_e32 v104, v0
	v_mov_b32_e32 v105, v0
	v_mov_b32_e32 v106, v0
	v_mov_b32_e32 v107, v0
	v_mov_b32_e32 v108, v0
	v_mov_b32_e32 v109, v0
	v_mov_b32_e32 v110, v0
	v_mov_b32_e32 v111, v0
	v_mov_b32_e32 v112, v0
	v_mov_b32_e32 v113, v0
	v_mov_b32_e32 v114, v0
	v_mov_b32_e32 v115, v0
	v_mov_b32_e32 v116, v0
	v_mov_b32_e32 v117, v0
	v_mov_b32_e32 v118, v0
	v_mov_b32_e32 v119, v0
	v_mov_b32_e32 v120, v0
	v_mov_b32_e32 v121, v0
	v_mov_b32_e32 v122, v0
	v_mov_b32_e32 v123, v0
	v_mov_b32_e32 v124, v0
	v_mov_b32_e32 v125, v0
	v_mov_b32_e32 v126, v0
	v_mov_b32_e32 v127, v0
	s_waitcnt vmcnt(6)
	s_and_saveexec_b64 s[70:71], s[4:5]
	s_cbranch_execz .LBB0_176
	s_barrier
.LBB0_176:
	s_or_b64 exec, exec, s[70:71]
	v_lshl_add_u64 v[138:139], v[130:131], 0, s[68:69]
	v_lshl_add_u64 v[140:141], v[132:133], 0, s[68:69]
	s_lshl_b32 s68, s75, 11
	s_lshl_b32 s69, s76, 8
	s_add_i32 s68, s68, s69
	s_ashr_i32 s69, s68, 31
	s_lshl_b64 s[68:69], s[68:69], 13
	s_lshl_b64 s[64:65], s[64:65], 12
	v_lshl_add_u64 v[142:143], v[130:131], 0, s[68:69]
	v_lshl_add_u64 v[144:145], v[132:133], 0, s[68:69]
	s_mov_b32 s70, -2
	s_mov_b64 s[68:69], s[56:57]
	s_barrier

; #define STAGE(Pp, BASE, br, kt) do { const u16* _g = (BASE) + ((long)(br) * K + (long)(kt) * BK); \
;     __builtin_amdgcn_global_load_lds((const unsigned*)(_g + voff0), (unsigned*)((char*)(Pp) + tb16), 16, 0, 0); \
;     __builtin_amdgcn_global_load_lds((const unsigned*)(_g + voff1), (unsigned*)((char*)(Pp) + tb16 + 8192), 16, 0, 0); } while (0)
; #define WAIT_V(n) asm volatile("s_waitcnt vmcnt(" #n ")" ::: "memory")
; #define BAR __builtin_amdgcn_s_barrier()
; template <int MODE> ...
;     ...
;   for (int wg0 = vb; wg0 < nwg; wg0 += nvb) {
;     int wgid = wg0;
;     { int q = nwg / NXCD, r = nwg % NXCD, xcd = wgid % NXCD, off = wgid / NXCD;
;       wgid = (xcd < r ? xcd * (q + 1) : r * (q + 1) + (xcd - r) * q) + off; }
;     int nig = WGM * nN, gid = wgid / nig, fm = gid * WGM, gsz = min(nM - fm, WGM);
;     int pm = fm + ((wgid % nig) % gsz), pn = (wgid % nig) / gsz, brow = pm * BM, bcol = pn * BM;
;     f32x4 acc[2][2][4][2] = {};
;     bf16x8 At[4][2], B0[2][2], B1[2][2];
;     ...
;     STAGE(SB(0, 0), Bt, bcol, 0); STAGE(SA(0, 0), A, brow, 0); STAGE(SB(0, 1), Bt, bcol + HALF, 0); STAGE(SA(0, 1), A, brow + HALF, 0);
;     STAGE(SB(1, 0), Bt, bcol, 1); STAGE(SA(1, 0), A, brow, 1); STAGE(SB(1, 1), Bt, bcol + HALF, 1);
;     WAIT_V(6);
;     if (wr == 1) BAR;
;     BAR;
.LBB0_483:
	s_ashr_i32 s63, s63, 3
	s_add_i32 s63, s67, s63
	s_ashr_i32 s64, s63, 31
	s_lshr_b32 s64, s64, 25
	s_add_i32 s64, s63, s64
	s_and_b32 s65, s64, 0xff80
	s_sub_i32 s63, s63, s65
	s_bfe_i32 s65, s63, 0x80000
	s_bfe_u32 s65, s65, 0x3000c
	s_add_i32 s65, s63, s65
	s_bfe_i32 s66, s65, 0x80000
	s_and_b32 s65, s65, 0xf8
	s_sub_i32 s63, s63, s65
	s_sext_i32_i8 s63, s63
	s_lshl_b32 s64, s64, 4
	s_sext_i32_i16 s67, s66
	s_and_b32 s64, s64, 0xfffff800
	s_lshl_b32 s63, s63, 8
	s_add_i32 s66, s63, s64
	s_lshl_b32 s63, s67, 5
	s_and_b32 s68, s63, 0xffffff00
	s_ashr_i32 s69, s68, 31
	s_lshl_b64 s[72:73], s[68:69], 13
	s_add_u32 s64, s33, s72
	v_readfirstlane_b32 s63, v147
	s_addc_u32 s65, s34, s73
	s_mov_b32 m0, s63
	v_readfirstlane_b32 s63, v148
	s_ashr_i32 s67, s66, 31
	global_load_lds_dwordx4 v132, s[64:65]
	s_mov_b32 m0, s63
	s_lshl_b64 s[74:75], s[66:67], 13
	v_lshl_add_u64 v[0:1], s[64:65], 0, v[132:133]
	v_lshl_add_u64 v[2:3], s[64:65], 0, v[134:135]
	global_load_lds_dwordx4 v134, s[64:65]
	s_add_u32 s64, s3, s74
	v_readfirstlane_b32 s63, v146
	s_addc_u32 s65, s15, s75
	s_mov_b32 m0, s63
	v_readfirstlane_b32 s63, v149
	global_load_lds_dwordx4 v132, s[64:65]
	s_mov_b32 m0, s63
	v_lshl_add_u64 v[4:5], s[64:65], 0, v[132:133]
	v_lshl_add_u64 v[6:7], s[64:65], 0, v[134:135]
	global_load_lds_dwordx4 v134, s[64:65]
	s_or_b32 s64, s68, 0x80
	s_ashr_i32 s65, s64, 31
	s_lshl_b64 s[64:65], s[64:65], 13
	s_add_u32 s64, s33, s64
	v_readfirstlane_b32 s63, v150
	s_addc_u32 s65, s34, s65
	s_mov_b32 m0, s63
	v_readfirstlane_b32 s63, v151
	global_load_lds_dwordx4 v132, s[64:65]
	s_mov_b32 m0, s63
	v_lshl_add_u64 v[8:9], s[64:65], 0, v[132:133]
	v_lshl_add_u64 v[10:11], s[64:65], 0, v[134:135]
	global_load_lds_dwordx4 v134, s[64:65]
	s_or_b32 s64, s66, 0x80
	s_ashr_i32 s65, s64, 31
	s_lshl_b64 s[70:71], s[64:65], 13
	s_add_u32 s70, s3, s70
	v_readfirstlane_b32 s63, v152
	s_addc_u32 s71, s15, s71
	s_mov_b32 m0, s63
	v_readfirstlane_b32 s63, v153
	global_load_lds_dwordx4 v132, s[70:71]
	s_mov_b32 m0, s63
	v_readfirstlane_b32 s63, v154
	global_load_lds_dwordx4 v134, s[70:71]
	v_lshl_add_u64 v[0:1], v[0:1], 0, s[12:13]
	s_mov_b32 m0, s63
	v_readfirstlane_b32 s63, v155
	global_load_lds_dwordx4 v[0:1], off
	v_lshl_add_u64 v[0:1], v[2:3], 0, s[12:13]
	s_mov_b32 m0, s63
	v_readfirstlane_b32 s63, v156
	global_load_lds_dwordx4 v[0:1], off
	v_lshl_add_u64 v[0:1], v[4:5], 0, s[12:13]
	s_mov_b32 m0, s63
	v_readfirstlane_b32 s63, v157
	global_load_lds_dwordx4 v[0:1], off
	v_lshl_add_u64 v[0:1], v[6:7], 0, s[12:13]
	s_mov_b32 m0, s63
	v_readfirstlane_b32 s63, v158
	global_load_lds_dwordx4 v[0:1], off
	v_lshl_add_u64 v[0:1], v[8:9], 0, s[12:13]
	s_mov_b32 m0, s63
	v_readfirstlane_b32 s63, v159
	global_load_lds_dwordx4 v[0:1], off
	v_lshl_add_u64 v[0:1], v[10:11], 0, s[12:13]
	s_mov_b32 m0, s63
	s_nop 0
	global_load_lds_dwordx4 v[0:1], off
	v_mov_b32_e32 v0, 0
	v_mov_b32_e32 v1, v0
	v_mov_b32_e32 v2, v0
	v_mov_b32_e32 v3, v0
	v_mov_b32_e32 v4, v0
	v_mov_b32_e32 v5, v0
	v_mov_b32_e32 v6, v0
	v_mov_b32_e32 v7, v0
	v_mov_b32_e32 v8, v0
	v_mov_b32_e32 v9, v0
	v_mov_b32_e32 v10, v0
	v_mov_b32_e32 v11, v0
	v_mov_b32_e32 v12, v0
	v_mov_b32_e32 v13, v0
	v_mov_b32_e32 v14, v0
	v_mov_b32_e32 v15, v0
	v_mov_b32_e32 v16, v0
	v_mov_b32_e32 v17, v0
	v_mov_b32_e32 v18, v0
	v_mov_b32_e32 v19, v0
	v_mov_b32_e32 v20, v0
	v_mov_b32_e32 v21, v0
	v_mov_b32_e32 v22, v0
	v_mov_b32_e32 v23, v0
	v_mov_b32_e32 v24, v0
	v_mov_b32_e32 v25, v0
	v_mov_b32_e32 v26, v0
	v_mov_b32_e32 v27, v0
	v_mov_b32_e32 v28, v0
	v_mov_b32_e32 v29, v0
	v_mov_b32_e32 v30, v0
	v_mov_b32_e32 v31, v0
	v_mov_b32_e32 v32, v0
	v_mov_b32_e32 v33, v0
	v_mov_b32_e32 v34, v0
	v_mov_b32_e32 v35, v0
	v_mov_b32_e32 v36, v0
	v_mov_b32_e32 v37, v0
	v_mov_b32_e32 v38, v0
	v_mov_b32_e32 v39, v0
	v_mov_b32_e32 v40, v0
	v_mov_b32_e32 v41, v0
	v_mov_b32_e32 v42, v0
	v_mov_b32_e32 v43, v0
	v_mov_b32_e32 v44, v0
	v_mov_b32_e32 v45, v0
	v_mov_b32_e32 v46, v0
	v_mov_b32_e32 v47, v0
	v_mov_b32_e32 v48, v0
	v_mov_b32_e32 v49, v0
	v_mov_b32_e32 v50, v0
	v_mov_b32_e32 v51, v0
	v_mov_b32_e32 v52, v0
	v_mov_b32_e32 v53, v0
	v_mov_b32_e32 v54, v0
	v_mov_b32_e32 v55, v0
	v_mov_b32_e32 v56, v0
	v_mov_b32_e32 v57, v0
	v_mov_b32_e32 v58, v0
	v_mov_b32_e32 v59, v0
	v_mov_b32_e32 v60, v0
	v_mov_b32_e32 v61, v0
	v_mov_b32_e32 v62, v0
	v_mov_b32_e32 v63, v0
	v_mov_b32_e32 v64, v0
	v_mov_b32_e32 v65, v0
	v_mov_b32_e32 v66, v0
	v_mov_b32_e32 v67, v0
	v_mov_b32_e32 v68, v0
	v_mov_b32_e32 v69, v0
	v_mov_b32_e32 v70, v0
	v_mov_b32_e32 v71, v0
	v_mov_b32_e32 v72, v0
	v_mov_b32_e32 v73, v0
	v_mov_b32_e32 v74, v0
	v_mov_b32_e32 v75, v0
	v_mov_b32_e32 v76, v0
	v_mov_b32_e32 v77, v0
	v_mov_b32_e32 v78, v0
	v_mov_b32_e32 v79, v0
	v_mov_b32_e32 v80, v0
	v_mov_b32_e32 v81, v0
	v_mov_b32_e32 v82, v0
	v_mov_b32_e32 v83, v0
	v_mov_b32_e32 v84, v0
	v_mov_b32_e32 v85, v0
	v_mov_b32_e32 v86, v0
	v_mov_b32_e32 v87, v0
	v_mov_b32_e32 v88, v0
	v_mov_b32_e32 v89, v0
	v_mov_b32_e32 v90, v0
	v_mov_b32_e32 v91, v0
	v_mov_b32_e32 v92, v0
	v_mov_b32_e32 v93, v0
	v_mov_b32_e32 v94, v0
	v_mov_b32_e32 v95, v0
	v_mov_b32_e32 v96, v0
	v_mov_b32_e32 v97, v0
	v_mov_b32_e32 v98, v0
	v_mov_b32_e32 v99, v0
	v_mov_b32_e32 v100, v0
	v_mov_b32_e32 v101, v0
	v_mov_b32_e32 v102, v0
	v_mov_b32_e32 v103, v0
	v_mov_b32_e32 v104, v0
	v_mov_b32_e32 v105, v0
	v_mov_b32_e32 v106, v0
	v_mov_b32_e32 v107, v0
	v_mov_b32_e32 v108, v0
	v_mov_b32_e32 v109, v0
	v_mov_b32_e32 v110, v0
	v_mov_b32_e32 v111, v0
	v_mov_b32_e32 v112, v0
	v_mov_b32_e32 v113, v0
	v_mov_b32_e32 v114, v0
	v_mov_b32_e32 v115, v0
	v_mov_b32_e32 v116, v0
	v_mov_b32_e32 v117, v0
	v_mov_b32_e32 v118, v0
	v_mov_b32_e32 v119, v0
	v_mov_b32_e32 v120, v0
	v_mov_b32_e32 v121, v0
	v_mov_b32_e32 v122, v0
	v_mov_b32_e32 v123, v0
	v_mov_b32_e32 v124, v0
	v_mov_b32_e32 v125, v0
	v_mov_b32_e32 v126, v0
	v_mov_b32_e32 v127, v0
	s_waitcnt vmcnt(6)
	s_and_saveexec_b64 s[76:77], s[4:5]
	s_cbranch_execz .LBB0_485
	s_barrier
.LBB0_485:
	s_or_b64 exec, exec, s[76:77]
	v_lshl_add_u64 v[136:137], v[130:131], 0, s[72:73]
	v_lshl_add_u64 v[138:139], v[128:129], 0, s[72:73]
	v_lshl_add_u64 v[140:141], v[130:131], 0, s[74:75]
	v_lshl_add_u64 v[142:143], v[128:129], 0, s[74:75]
	s_mov_b32 s63, -2
	s_mov_b64 s[72:73], s[56:57]
	s_barrier

; #define STAGE(Pp, BASE, br, kt) do { const u16* _g = (BASE) + ((long)(br) * K + (long)(kt) * BK); \
;     __builtin_amdgcn_global_load_lds((const unsigned*)(_g + voff0), (unsigned*)((char*)(Pp) + tb16), 16, 0, 0); \
;     __builtin_amdgcn_global_load_lds((const unsigned*)(_g + voff1), (unsigned*)((char*)(Pp) + tb16 + 8192), 16, 0, 0); } while (0)
; #define WAIT_V(n) asm volatile("s_waitcnt vmcnt(" #n ")" ::: "memory")
; #define BAR __builtin_amdgcn_s_barrier()
; template <int MODE> ...
;     ...
;   for (int wg0 = vb; wg0 < nwg; wg0 += nvb) {
;     int wgid = wg0;
;     { int q = nwg / NXCD, r = nwg % NXCD, xcd = wgid % NXCD, off = wgid / NXCD;
;       wgid = (xcd < r ? xcd * (q + 1) : r * (q + 1) + (xcd - r) * q) + off; }
;     int nig = WGM * nN, gid = wgid / nig, fm = gid * WGM, gsz = min(nM - fm, WGM);
;     int pm = fm + ((wgid % nig) % gsz), pn = (wgid % nig) / gsz, brow = pm * BM, bcol = pn * BM;
;     f32x4 acc[2][2][4][2] = {};
;     bf16x8 At[4][2], B0[2][2], B1[2][2];
;     ...
;     STAGE(SB(0, 0), Bt, bcol, 0); STAGE(SA(0, 0), A, brow, 0); STAGE(SB(0, 1), Bt, bcol + HALF, 0); STAGE(SA(0, 1), A, brow + HALF, 0);
;     STAGE(SB(1, 0), Bt, bcol, 1); STAGE(SA(1, 0), A, brow, 1); STAGE(SB(1, 1), Bt, bcol + HALF, 1);
;     WAIT_V(6);
;     if (wr == 1) BAR;
;     BAR;
.LBB0_588:
	s_ashr_i32 s8, s85, 31
	s_lshr_b32 s8, s8, 29
	s_add_i32 s8, s85, s8
	s_ashr_i32 s9, s8, 3
	s_and_b32 s8, s8, -8
	s_sub_i32 s8, s85, s8
	s_cmp_lt_i32 s8, 0
	s_cselect_b32 s10, s72, 0x158
	s_mul_i32 s8, s10, s8
	s_add_i32 s8, s8, s9
	s_mul_hi_i32 s9, s8, 0x2fa0be83
	s_lshr_b32 s10, s9, 31
	s_ashr_i32 s9, s9, 7
	s_add_i32 s9, s9, s10
	s_lshl_b32 s86, s9, 3
	s_mulk_i32 s9, 0x2b0
	s_sub_i32 s8, s8, s9
	s_sext_i32_i16 s9, s8
	s_bfe_u32 s9, s9, 0x3001c
	s_add_i32 s9, s8, s9
	s_sext_i32_i16 s10, s9
	s_and_b32 s9, s9, 0xfff8
	s_sub_i32 s8, s8, s9
	s_sext_i32_i16 s8, s8
	s_ashr_i32 s34, s10, 3
	s_add_i32 s86, s86, s8
	s_lshl_b32 s8, s34, 8
	s_ashr_i32 s9, s8, 31
	s_lshl_b32 s64, s86, 8
	s_lshl_b64 s[10:11], s[8:9], 13
	s_add_u32 s66, s16, s10
	v_readfirstlane_b32 s9, v151
	s_addc_u32 s67, s17, s11
	s_mov_b32 m0, s9
	v_readfirstlane_b32 s9, v152
	global_load_lds_dwordx4 v134, s[66:67]
	s_mov_b32 m0, s9
	s_ashr_i32 s65, s64, 31
	v_lshl_add_u64 v[0:1], s[66:67], 0, v[134:135]
	v_lshl_add_u64 v[2:3], s[66:67], 0, v[136:137]
	global_load_lds_dwordx4 v136, s[66:67]
	s_lshl_b64 s[66:67], s[64:65], 13
	s_add_u32 s68, s56, s66
	v_readfirstlane_b32 s9, v150
	s_addc_u32 s69, s57, s67
	s_mov_b32 m0, s9
	v_readfirstlane_b32 s9, v153
	s_bitset1_b32 s8, 7
	global_load_lds_dwordx4 v134, s[68:69]
	s_mov_b32 m0, s9
	s_ashr_i32 s9, s8, 31
	s_lshl_b64 s[8:9], s[8:9], 13
	s_add_u32 s8, s16, s8
	v_readfirstlane_b32 s35, v154
	global_load_lds_dwordx4 v136, s[68:69]
	s_addc_u32 s9, s17, s9
	s_mov_b32 m0, s35
	v_readfirstlane_b32 s35, v155
	global_load_lds_dwordx4 v134, s[8:9]
	s_mov_b32 m0, s35
	v_lshl_add_u64 v[8:9], s[8:9], 0, v[134:135]
	v_lshl_add_u64 v[10:11], s[8:9], 0, v[136:137]
	global_load_lds_dwordx4 v136, s[8:9]
	s_or_b32 s8, s64, 0x80
	s_ashr_i32 s9, s8, 31
	s_lshl_b64 s[8:9], s[8:9], 13
	s_add_u32 s8, s56, s8
	v_readfirstlane_b32 s35, v156
	s_addc_u32 s9, s57, s9
	s_mov_b32 m0, s35
	v_readfirstlane_b32 s35, v157
	global_load_lds_dwordx4 v134, s[8:9]
	s_mov_b32 m0, s35
	v_readfirstlane_b32 s35, v158
	global_load_lds_dwordx4 v136, s[8:9]
	v_lshl_add_u64 v[0:1], v[0:1], 0, s[36:37]
	s_mov_b32 m0, s35
	v_readfirstlane_b32 s35, v159
	v_lshl_add_u64 v[4:5], s[68:69], 0, v[134:135]
	global_load_lds_dwordx4 v[0:1], off
	v_lshl_add_u64 v[0:1], v[2:3], 0, s[36:37]
	s_mov_b32 m0, s35
	v_readfirstlane_b32 s35, v160
	v_lshl_add_u64 v[6:7], s[68:69], 0, v[136:137]
	global_load_lds_dwordx4 v[0:1], off
	v_lshl_add_u64 v[0:1], v[4:5], 0, s[36:37]
	s_mov_b32 m0, s35
	v_readfirstlane_b32 s35, v161
	global_load_lds_dwordx4 v[0:1], off
	v_lshl_add_u64 v[0:1], v[6:7], 0, s[36:37]
	s_mov_b32 m0, s35
	v_readfirstlane_b32 s35, v162
	global_load_lds_dwordx4 v[0:1], off
	v_lshl_add_u64 v[0:1], v[8:9], 0, s[36:37]
	s_mov_b32 m0, s35
	v_readfirstlane_b32 s35, v163
	global_load_lds_dwordx4 v[0:1], off
	v_lshl_add_u64 v[0:1], v[10:11], 0, s[36:37]
	s_mov_b32 m0, s35
	s_nop 0
	global_load_lds_dwordx4 v[0:1], off
	v_mov_b32_e32 v0, 0
	v_mov_b32_e32 v1, v0
	v_mov_b32_e32 v2, v0
	v_mov_b32_e32 v3, v0
	v_mov_b32_e32 v4, v0
	v_mov_b32_e32 v5, v0
	v_mov_b32_e32 v6, v0
	v_mov_b32_e32 v7, v0
	v_mov_b32_e32 v8, v0
	v_mov_b32_e32 v9, v0
	v_mov_b32_e32 v10, v0
	v_mov_b32_e32 v11, v0
	v_mov_b32_e32 v12, v0
	v_mov_b32_e32 v13, v0
	v_mov_b32_e32 v14, v0
	v_mov_b32_e32 v15, v0
	v_mov_b32_e32 v16, v0
	v_mov_b32_e32 v17, v0
	v_mov_b32_e32 v18, v0
	v_mov_b32_e32 v19, v0
	v_mov_b32_e32 v20, v0
	v_mov_b32_e32 v21, v0
	v_mov_b32_e32 v22, v0
	v_mov_b32_e32 v23, v0
	v_mov_b32_e32 v24, v0
	v_mov_b32_e32 v25, v0
	v_mov_b32_e32 v26, v0
	v_mov_b32_e32 v27, v0
	v_mov_b32_e32 v28, v0
	v_mov_b32_e32 v29, v0
	v_mov_b32_e32 v30, v0
	v_mov_b32_e32 v31, v0
	v_mov_b32_e32 v32, v0
	v_mov_b32_e32 v33, v0
	v_mov_b32_e32 v34, v0
	v_mov_b32_e32 v35, v0
	v_mov_b32_e32 v36, v0
	v_mov_b32_e32 v37, v0
	v_mov_b32_e32 v38, v0
	v_mov_b32_e32 v39, v0
	v_mov_b32_e32 v40, v0
	v_mov_b32_e32 v41, v0
	v_mov_b32_e32 v42, v0
	v_mov_b32_e32 v43, v0
	v_mov_b32_e32 v44, v0
	v_mov_b32_e32 v45, v0
	v_mov_b32_e32 v46, v0
	v_mov_b32_e32 v47, v0
	v_mov_b32_e32 v48, v0
	v_mov_b32_e32 v49, v0
	v_mov_b32_e32 v50, v0
	v_mov_b32_e32 v51, v0
	v_mov_b32_e32 v56, v0
	v_mov_b32_e32 v57, v0
	v_mov_b32_e32 v58, v0
	v_mov_b32_e32 v59, v0
	v_mov_b32_e32 v72, v0
	v_mov_b32_e32 v73, v0
	v_mov_b32_e32 v74, v0
	v_mov_b32_e32 v75, v0
	v_mov_b32_e32 v88, v0
	v_mov_b32_e32 v89, v0
	v_mov_b32_e32 v90, v0
	v_mov_b32_e32 v91, v0
	v_mov_b32_e32 v96, v0
	v_mov_b32_e32 v97, v0
	v_mov_b32_e32 v98, v0
	v_mov_b32_e32 v99, v0
	v_mov_b32_e32 v100, v0
	v_mov_b32_e32 v101, v0
	v_mov_b32_e32 v102, v0
	v_mov_b32_e32 v103, v0
	v_mov_b32_e32 v104, v0
	v_mov_b32_e32 v105, v0
	v_mov_b32_e32 v106, v0
	v_mov_b32_e32 v107, v0
	v_mov_b32_e32 v108, v0
	v_mov_b32_e32 v109, v0
	v_mov_b32_e32 v110, v0
	v_mov_b32_e32 v111, v0
	v_mov_b32_e32 v112, v0
	v_mov_b32_e32 v113, v0
	v_mov_b32_e32 v114, v0
	v_mov_b32_e32 v115, v0
	v_mov_b32_e32 v116, v0
	v_mov_b32_e32 v117, v0
	v_mov_b32_e32 v118, v0
	v_mov_b32_e32 v119, v0
	v_mov_b32_e32 v120, v0
	v_mov_b32_e32 v121, v0
	v_mov_b32_e32 v122, v0
	v_mov_b32_e32 v123, v0
	v_mov_b32_e32 v124, v0
	v_mov_b32_e32 v125, v0
	v_mov_b32_e32 v126, v0
	v_mov_b32_e32 v127, v0
	v_mov_b32_e32 v52, v0
	v_mov_b32_e32 v53, v0
	v_mov_b32_e32 v54, v0
	v_mov_b32_e32 v55, v0
	v_mov_b32_e32 v60, v0
	v_mov_b32_e32 v61, v0
	v_mov_b32_e32 v62, v0
	v_mov_b32_e32 v63, v0
	v_mov_b32_e32 v64, v0
	v_mov_b32_e32 v65, v0
	v_mov_b32_e32 v66, v0
	v_mov_b32_e32 v67, v0
	v_mov_b32_e32 v68, v0
	v_mov_b32_e32 v69, v0
	v_mov_b32_e32 v70, v0
	v_mov_b32_e32 v71, v0
	v_mov_b32_e32 v76, v0
	v_mov_b32_e32 v77, v0
	v_mov_b32_e32 v78, v0
	v_mov_b32_e32 v79, v0
	v_mov_b32_e32 v80, v0
	v_mov_b32_e32 v81, v0
	v_mov_b32_e32 v82, v0
	v_mov_b32_e32 v83, v0
	v_mov_b32_e32 v84, v0
	v_mov_b32_e32 v85, v0
	v_mov_b32_e32 v86, v0
	v_mov_b32_e32 v87, v0
	v_mov_b32_e32 v92, v0
	v_mov_b32_e32 v93, v0
	v_mov_b32_e32 v94, v0
	v_mov_b32_e32 v95, v0
	s_waitcnt vmcnt(6)
	s_and_saveexec_b64 s[68:69], s[4:5]
	s_cbranch_execz .LBB0_590
	s_barrier
.LBB0_590:
	s_or_b64 exec, exec, s[68:69]
	v_lshl_add_u64 v[138:139], v[146:147], 0, s[10:11]
	v_lshl_add_u64 v[140:141], v[252:253], 0, s[10:11]
	v_lshl_add_u64 v[142:143], v[146:147], 0, s[66:67]
	v_lshl_add_u64 v[144:145], v[252:253], 0, s[66:67]
	s_mov_b32 s35, -2
	s_mov_b64 s[10:11], s[56:57]
	s_barrier

; #define STAGE(Pp, BASE, br, kt) do { const u16* _g = (BASE) + ((long)(br) * K + (long)(kt) * BK); \
;     __builtin_amdgcn_global_load_lds((const unsigned*)(_g + voff0), (unsigned*)((char*)(Pp) + tb16), 16, 0, 0); \
;     __builtin_amdgcn_global_load_lds((const unsigned*)(_g + voff1), (unsigned*)((char*)(Pp) + tb16 + 8192), 16, 0, 0); } while (0)
; #define WAIT_V(n) asm volatile("s_waitcnt vmcnt(" #n ")" ::: "memory")
; #define BAR __builtin_amdgcn_s_barrier()
; template <int MODE> ...
;     ...
;   for (int wg0 = vb; wg0 < nwg; wg0 += nvb) {
;     int wgid = wg0;
;     { int q = nwg / NXCD, r = nwg % NXCD, xcd = wgid % NXCD, off = wgid / NXCD;
;       wgid = (xcd < r ? xcd * (q + 1) : r * (q + 1) + (xcd - r) * q) + off; }
;     int nig = WGM * nN, gid = wgid / nig, fm = gid * WGM, gsz = min(nM - fm, WGM);
;     int pm = fm + ((wgid % nig) % gsz), pn = (wgid % nig) / gsz, brow = pm * BM, bcol = pn * BM;
;     f32x4 acc[2][2][4][2] = {};
;     bf16x8 At[4][2], B0[2][2], B1[2][2];
;     ...
;     STAGE(SB(0, 0), Bt, bcol, 0); STAGE(SA(0, 0), A, brow, 0); STAGE(SB(0, 1), Bt, bcol + HALF, 0); STAGE(SA(0, 1), A, brow + HALF, 0);
;     STAGE(SB(1, 0), Bt, bcol, 1); STAGE(SA(1, 0), A, brow, 1); STAGE(SB(1, 1), Bt, bcol + HALF, 1);
;     WAIT_V(6);
;     if (wr == 1) BAR;
;     BAR;
.LBB0_845:
	s_ashr_i32 s45, s45, 3
	s_add_i32 s45, s49, s45
	s_ashr_i32 s46, s45, 31
	s_lshr_b32 s46, s46, 25
	s_add_i32 s46, s45, s46
	s_and_b32 s47, s46, 0xff80
	s_sub_i32 s45, s45, s47
	s_bfe_i32 s47, s45, 0x80000
	s_bfe_u32 s47, s47, 0x3000c
	s_add_i32 s47, s45, s47
	s_bfe_i32 s48, s47, 0x80000
	s_and_b32 s47, s47, 0xf8
	s_sub_i32 s45, s45, s47
	s_sext_i32_i16 s48, s48
	s_sext_i32_i8 s45, s45
	s_lshl_b32 s46, s46, 4
	s_ashr_i32 s49, s48, 3
	s_and_b32 s46, s46, 0xfffff800
	s_lshl_b32 s45, s45, 8
	s_add_i32 s48, s45, s46
	s_lshl_b32 s50, s49, 8
	s_mul_i32 s62, s49, 0x560000
	s_mul_hi_i32 s63, s50, 0x5600
	s_add_u32 s46, s33, s62
	v_readfirstlane_b32 s45, v153
	s_addc_u32 s47, s34, s63
	s_mov_b32 m0, s45
	v_readfirstlane_b32 s45, v154
	global_load_lds_dwordx4 v134, s[46:47]
	s_mov_b32 m0, s45
	s_mul_i32 s64, s48, 0x5600
	v_lshl_add_u64 v[0:1], s[46:47], 0, v[134:135]
	v_lshl_add_u64 v[2:3], s[46:47], 0, v[136:137]
	global_load_lds_dwordx4 v136, s[46:47]
	s_mul_hi_i32 s65, s48, 0x5600
	s_add_u32 s46, s3, s64
	v_readfirstlane_b32 s45, v152
	s_addc_u32 s47, s15, s65
	s_mov_b32 m0, s45
	v_readfirstlane_b32 s45, v155
	global_load_lds_dwordx4 v134, s[46:47]
	s_mov_b32 m0, s45
	v_lshl_add_u64 v[4:5], s[46:47], 0, v[134:135]
	v_lshl_add_u64 v[6:7], s[46:47], 0, v[136:137]
	global_load_lds_dwordx4 v136, s[46:47]
	s_mul_i32 s46, s49, 0x2b0000
	s_ashr_i32 s47, s46, 31
	s_lshl_b64 s[66:67], s[46:47], 1
	s_add_u32 s45, s33, s66
	s_addc_u32 s49, s34, s67
	s_add_u32 s46, s45, 0x2b0000
	v_readfirstlane_b32 s51, v156
	s_addc_u32 s47, s49, 0
	s_mov_b32 m0, s51
	v_readfirstlane_b32 s51, v157
	global_load_lds_dwordx4 v134, s[46:47]
	s_mov_b32 m0, s51
	v_lshl_add_u64 v[0:1], v[0:1], 0, s[16:17]
	global_load_lds_dwordx4 v136, s[46:47]
	s_or_b32 s46, s48, 0x80
	s_mul_i32 s51, s46, 0x5600
	s_mul_hi_i32 s47, s46, 0x5600
	s_add_u32 s60, s3, s51
	s_addc_u32 s61, s15, s47
	v_readfirstlane_b32 s47, v158
	s_mov_b32 m0, s47
	v_readfirstlane_b32 s47, v159
	global_load_lds_dwordx4 v134, s[60:61]
	s_mov_b32 m0, s47
	v_readfirstlane_b32 s47, v160
	global_load_lds_dwordx4 v136, s[60:61]
	s_mov_b32 m0, s47
	v_readfirstlane_b32 s47, v161
	global_load_lds_dwordx4 v[0:1], off
	v_lshl_add_u64 v[0:1], v[2:3], 0, s[16:17]
	s_mov_b32 m0, s47
	v_readfirstlane_b32 s47, v162
	global_load_lds_dwordx4 v[0:1], off
	v_lshl_add_u64 v[0:1], v[4:5], 0, s[16:17]
	s_mov_b32 m0, s47
	v_readfirstlane_b32 s47, v163
	global_load_lds_dwordx4 v[0:1], off
	v_lshl_add_u64 v[0:1], v[6:7], 0, s[16:17]
	s_mov_b32 m0, s47
	s_add_u32 s68, s45, 0x2b0080
	v_readfirstlane_b32 s45, v165
	global_load_lds_dwordx4 v[0:1], off
	s_addc_u32 s69, s49, 0
	s_mov_b32 m0, s45
	v_readfirstlane_b32 s45, v166
	global_load_lds_dwordx4 v134, s[68:69]
	s_mov_b32 m0, s45
	s_nop 0
	global_load_lds_dwordx4 v136, s[68:69]
	v_mov_b32_e32 v0, 0
	v_mov_b32_e32 v1, v0
	v_mov_b32_e32 v2, v0
	v_mov_b32_e32 v3, v0
	v_mov_b32_e32 v4, v0
	v_mov_b32_e32 v5, v0
	v_mov_b32_e32 v6, v0
	v_mov_b32_e32 v7, v0
	v_mov_b32_e32 v8, v0
	v_mov_b32_e32 v9, v0
	v_mov_b32_e32 v10, v0
	v_mov_b32_e32 v11, v0
	v_mov_b32_e32 v12, v0
	v_mov_b32_e32 v13, v0
	v_mov_b32_e32 v14, v0
	v_mov_b32_e32 v15, v0
	v_mov_b32_e32 v16, v0
	v_mov_b32_e32 v17, v0
	v_mov_b32_e32 v18, v0
	v_mov_b32_e32 v19, v0
	v_mov_b32_e32 v20, v0
	v_mov_b32_e32 v21, v0
	v_mov_b32_e32 v22, v0
	v_mov_b32_e32 v23, v0
	v_mov_b32_e32 v24, v0
	v_mov_b32_e32 v25, v0
	v_mov_b32_e32 v26, v0
	v_mov_b32_e32 v27, v0
	v_mov_b32_e32 v28, v0
	v_mov_b32_e32 v29, v0
	v_mov_b32_e32 v30, v0
	v_mov_b32_e32 v31, v0
	v_mov_b32_e32 v32, v0
	v_mov_b32_e32 v33, v0
	v_mov_b32_e32 v34, v0
	v_mov_b32_e32 v35, v0
	v_mov_b32_e32 v36, v0
	v_mov_b32_e32 v37, v0
	v_mov_b32_e32 v38, v0
	v_mov_b32_e32 v39, v0
	v_mov_b32_e32 v40, v0
	v_mov_b32_e32 v41, v0
	v_mov_b32_e32 v42, v0
	v_mov_b32_e32 v43, v0
	v_mov_b32_e32 v44, v0
	v_mov_b32_e32 v45, v0
	v_mov_b32_e32 v46, v0
	v_mov_b32_e32 v47, v0
	v_mov_b32_e32 v48, v0
	v_mov_b32_e32 v49, v0
	v_mov_b32_e32 v50, v0
	v_mov_b32_e32 v51, v0
	v_mov_b32_e32 v52, v0
	v_mov_b32_e32 v53, v0
	v_mov_b32_e32 v54, v0
	v_mov_b32_e32 v55, v0
	v_mov_b32_e32 v56, v0
	v_mov_b32_e32 v57, v0
	v_mov_b32_e32 v58, v0
	v_mov_b32_e32 v59, v0
	v_mov_b32_e32 v60, v0
	v_mov_b32_e32 v61, v0
	v_mov_b32_e32 v62, v0
	v_mov_b32_e32 v63, v0
	v_mov_b32_e32 v64, v0
	v_mov_b32_e32 v65, v0
	v_mov_b32_e32 v66, v0
	v_mov_b32_e32 v67, v0
	v_mov_b32_e32 v68, v0
	v_mov_b32_e32 v69, v0
	v_mov_b32_e32 v70, v0
	v_mov_b32_e32 v71, v0
	v_mov_b32_e32 v72, v0
	v_mov_b32_e32 v73, v0
	v_mov_b32_e32 v74, v0
	v_mov_b32_e32 v75, v0
	v_mov_b32_e32 v76, v0
	v_mov_b32_e32 v77, v0
	v_mov_b32_e32 v78, v0
	v_mov_b32_e32 v79, v0
	v_mov_b32_e32 v80, v0
	v_mov_b32_e32 v81, v0
	v_mov_b32_e32 v82, v0
	v_mov_b32_e32 v83, v0
	v_mov_b32_e32 v84, v0
	v_mov_b32_e32 v85, v0
	v_mov_b32_e32 v86, v0
	v_mov_b32_e32 v87, v0
	v_mov_b32_e32 v88, v0
	v_mov_b32_e32 v89, v0
	v_mov_b32_e32 v90, v0
	v_mov_b32_e32 v91, v0
	v_mov_b32_e32 v92, v0
	v_mov_b32_e32 v93, v0
	v_mov_b32_e32 v94, v0
	v_mov_b32_e32 v95, v0
	v_mov_b32_e32 v96, v0
	v_mov_b32_e32 v97, v0
	v_mov_b32_e32 v98, v0
	v_mov_b32_e32 v99, v0
	v_mov_b32_e32 v100, v0
	v_mov_b32_e32 v101, v0
	v_mov_b32_e32 v102, v0
	v_mov_b32_e32 v103, v0
	v_mov_b32_e32 v104, v0
	v_mov_b32_e32 v105, v0
	v_mov_b32_e32 v106, v0
	v_mov_b32_e32 v107, v0
	v_mov_b32_e32 v108, v0
	v_mov_b32_e32 v109, v0
	v_mov_b32_e32 v110, v0
	v_mov_b32_e32 v111, v0
	v_mov_b32_e32 v112, v0
	v_mov_b32_e32 v113, v0
	v_mov_b32_e32 v114, v0
	v_mov_b32_e32 v115, v0
	v_mov_b32_e32 v116, v0
	v_mov_b32_e32 v117, v0
	v_mov_b32_e32 v118, v0
	v_mov_b32_e32 v119, v0
	v_mov_b32_e32 v120, v0
	v_mov_b32_e32 v121, v0
	v_mov_b32_e32 v122, v0
	v_mov_b32_e32 v123, v0
	v_mov_b32_e32 v124, v0
	v_mov_b32_e32 v125, v0
	v_mov_b32_e32 v126, v0
	v_mov_b32_e32 v127, v0
	s_waitcnt vmcnt(6)
	s_and_saveexec_b64 s[68:69], s[4:5]
	s_cbranch_execz .LBB0_847
	s_barrier
.LBB0_847:
	s_or_b64 exec, exec, s[68:69]
	s_ashr_i32 s51, s50, 31
	s_ashr_i32 s49, s48, 31
	s_ashr_i32 s47, s46, 31
	v_lshl_add_u64 v[138:139], v[130:131], 0, s[62:63]
	v_lshl_add_u64 v[140:141], v[132:133], 0, s[62:63]
	v_lshl_add_u64 v[142:143], v[130:131], 0, s[66:67]
	v_lshl_add_u64 v[144:145], v[132:133], 0, s[66:67]
	v_lshl_add_u64 v[146:147], v[130:131], 0, s[64:65]
	v_lshl_add_u64 v[148:149], v[132:133], 0, s[64:65]
	s_mov_b32 s45, -2
	s_mov_b64 s[62:63], s[56:57]
	s_barrier
